# ResNorm epilogue part1: base loads pipelined two row-groups ahead instead of load-wait-store chain
# speedup vs baseline: 1.0778x; 1.0778x over previous
.LBB0_832:
	s_lshr_b32 s26, s26, 2
	s_mulk_i32 s26, 0x1800
	s_lshl_b32 s38, s35, 5
	s_addk_i32 s26, 0x1800
	s_and_b64 s[2:3], s[2:3], exec
	s_cselect_b32 s26, 0, s26
	s_lshl_b32 s2, s62, 8
	s_or_b32 s2, s2, s38
	v_lshrrev_b32_e32 v128, 2, v192
	v_and_or_b32 v210, v128, 12, s2
	s_lshl_b64 s[2:3], s[26:27], 2
	v_readlane_b32 s38, v255, 12
	v_ashrrev_i32_e32 v161, 31, v160
	v_readlane_b32 s39, v255, 13
	s_add_u32 s38, s38, s2
	v_ashrrev_i32_e32 v211, 31, v210
	v_lshlrev_b64 v[130:131], 10, v[160:161]
	s_addc_u32 s39, s39, s3
	v_lshl_add_u64 v[206:207], v[130:131], 0, v[210:211]
	v_lshl_add_u64 v[128:129], v[210:211], 2, s[38:39]
	v_lshlrev_b64 v[150:151], 2, v[206:207]
	global_load_dwordx4 v[140:143], v[128:129], off
	global_load_dwordx4 v[136:139], v[128:129], off offset:64
	global_load_dwordx4 v[132:135], v[128:129], off offset:512
	s_nop 0
	global_load_dwordx4 v[128:131], v[128:129], off offset:576
	s_add_u32 s36, s76, s36
	v_cndmask_b32_e64 v152, 0, 1, s[20:21]
	s_addc_u32 s37, s77, s37
	v_readlane_b32 s52, v254, 49
	v_cmp_ne_u32_e64 s[38:39], 1, v152
	v_readlane_b32 s53, v254, 50
	v_readlane_b32 s20, v255, 16
	v_readlane_b32 s21, v255, 17
	s_lshl_b32 s26, s35, 2
	v_cmp_gt_u32_e64 s[40:41], 16, v224
	s_add_i32 s26, s26, 0
	s_movk_i32 s42, 0x210
	v_lshl_add_u64 v[208:209], s[36:37], 0, v[150:151]
	v_or_b32_e32 v184, 16, v160
	v_ashrrev_i32_e32 v185, 31, v184
	v_lshlrev_b64 v[250:251], 10, v[184:185]
	v_lshl_add_u64 v[202:203], v[250:251], 0, v[210:211]
	v_lshlrev_b64 v[250:251], 2, v[202:203]
	v_lshl_add_u64 v[204:205], s[36:37], 0, v[250:251]
	v_or_b32_e32 v184, 32, v160
	v_ashrrev_i32_e32 v185, 31, v184
	v_lshlrev_b64 v[250:251], 10, v[184:185]
	v_lshl_add_u64 v[198:199], v[250:251], 0, v[210:211]
	v_lshlrev_b64 v[250:251], 2, v[198:199]
	v_lshl_add_u64 v[200:201], s[36:37], 0, v[250:251]
	v_or_b32_e32 v184, 48, v160
	v_ashrrev_i32_e32 v185, 31, v184
	v_lshlrev_b64 v[250:251], 10, v[184:185]
	v_lshl_add_u64 v[194:195], v[250:251], 0, v[210:211]
	v_lshlrev_b64 v[250:251], 2, v[194:195]
	v_lshl_add_u64 v[196:197], s[36:37], 0, v[250:251]
	v_add_u32_e32 v184, 0x80, v160
	v_ashrrev_i32_e32 v185, 31, v184
	v_lshlrev_b64 v[250:251], 10, v[184:185]
	v_lshl_add_u64 v[174:175], v[250:251], 0, v[210:211]
	v_lshlrev_b64 v[250:251], 2, v[174:175]
	v_lshl_add_u64 v[176:177], s[36:37], 0, v[250:251]
	v_add_u32_e32 v184, 0x90, v160
	v_ashrrev_i32_e32 v185, 31, v184
	v_lshlrev_b64 v[250:251], 10, v[184:185]
	v_lshl_add_u64 v[170:171], v[250:251], 0, v[210:211]
	v_lshlrev_b64 v[250:251], 2, v[170:171]
	v_lshl_add_u64 v[172:173], s[36:37], 0, v[250:251]
	v_add_u32_e32 v184, 0xa0, v160
	v_ashrrev_i32_e32 v185, 31, v184
	v_lshlrev_b64 v[250:251], 10, v[184:185]
	v_lshl_add_u64 v[166:167], v[250:251], 0, v[210:211]
	v_lshlrev_b64 v[250:251], 2, v[166:167]
	v_lshl_add_u64 v[168:169], s[36:37], 0, v[250:251]
	v_add_u32_e32 v184, 0xb0, v160
	v_ashrrev_i32_e32 v185, 31, v184
	v_lshlrev_b64 v[250:251], 10, v[184:185]
	v_lshl_add_u64 v[162:163], v[250:251], 0, v[210:211]
	v_lshlrev_b64 v[250:251], 2, v[162:163]
	v_lshl_add_u64 v[164:165], s[36:37], 0, v[250:251]
	v_lshlrev_b64 v[250:251], 2, v[206:207]
	v_lshl_add_u64 v[212:213], s[0:1], 0, v[250:251]
	global_load_dwordx4 v[226:229], v[212:213], off
	global_load_dwordx4 v[230:233], v[212:213], off offset:64
	global_load_dwordx4 v[234:237], v[212:213], off offset:512
	global_load_dwordx4 v[238:241], v[212:213], off offset:576
	v_lshlrev_b64 v[250:251], 2, v[202:203]
	v_lshl_add_u64 v[212:213], s[0:1], 0, v[250:251]
	global_load_dwordx4 v[242:245], v[212:213], off
	global_load_dwordx4 v[246:249], v[212:213], off offset:64
	global_load_dwordx4 v[180:183], v[212:213], off offset:512
	global_load_dwordx4 v[188:191], v[212:213], off offset:576
	s_waitcnt vmcnt(4)
	v_pk_fma_f32 v[158:159], v[126:127], v[142:143], v[228:229]
	v_pk_fma_f32 v[156:157], v[124:125], v[140:141], v[226:227]
	v_pk_fma_f32 v[154:155], v[122:123], v[138:139], v[232:233]
	v_pk_fma_f32 v[152:153], v[120:121], v[136:137], v[230:231]
	v_pk_fma_f32 v[150:151], v[118:119], v[134:135], v[236:237]
	v_pk_fma_f32 v[148:149], v[116:117], v[132:133], v[234:235]
	v_pk_fma_f32 v[118:119], v[114:115], v[130:131], v[240:241]
	v_pk_fma_f32 v[116:117], v[112:113], v[128:129], v[238:239]
	s_and_b64 vcc, exec, s[38:39]
	s_cbranch_vccnz .Lrn_ns_0
	global_store_dwordx4 v[208:209], v[156:159], off
	global_store_dwordx4 v[208:209], v[152:155], off offset:64
	global_store_dwordx4 v[208:209], v[148:151], off offset:512
	global_store_dwordx4 v[208:209], v[116:119], off offset:576
.Lrn_ns_0:
	v_lshlrev_b64 v[250:251], 2, v[198:199]
	v_lshl_add_u64 v[212:213], s[0:1], 0, v[250:251]
	global_load_dwordx4 v[226:229], v[212:213], off
	global_load_dwordx4 v[230:233], v[212:213], off offset:64
	global_load_dwordx4 v[234:237], v[212:213], off offset:512
	global_load_dwordx4 v[238:241], v[212:213], off offset:576
	v_and_b32_e32 v114, 64, v219
	v_xor_b32_e32 v113, 16, v219
	v_add_u32_e32 v114, 64, v114
	v_xor_b32_e32 v115, 32, v219
	v_cmp_lt_i32_e32 vcc, v113, v114
	s_nop 1
	v_cndmask_b32_e32 v113, v219, v113, vcc
	v_cmp_lt_i32_e32 vcc, v115, v114
	v_lshlrev_b32_e32 v120, 2, v113
	s_nop 0
	v_cndmask_b32_e32 v114, v219, v115, vcc
	v_lshlrev_b32_e32 v121, 2, v114
	v_mul_f32_e32 v186, v157, v157
	v_mul_f32_e32 v187, v159, v159
	v_fmac_f32_e32 v186, v156, v156
	v_fmac_f32_e32 v187, v158, v158
	v_add_f32_e32 v186, v186, v187
	v_mul_f32_e32 v187, v153, v153
	v_mul_f32_e32 v193, v155, v155
	v_fmac_f32_e32 v187, v152, v152
	v_fmac_f32_e32 v193, v154, v154
	v_add_f32_e32 v187, v187, v193
	v_add_f32_e32 v186, v186, v187
	v_mul_f32_e32 v187, v149, v149
	v_mul_f32_e32 v193, v151, v151
	v_fmac_f32_e32 v187, v148, v148
	v_fmac_f32_e32 v193, v150, v150
	v_add_f32_e32 v187, v187, v193
	v_add_f32_e32 v186, v186, v187
	v_mul_f32_e32 v187, v117, v117
	v_mul_f32_e32 v193, v119, v119
	v_fmac_f32_e32 v187, v116, v116
	v_fmac_f32_e32 v193, v118, v118
	v_add_f32_e32 v187, v187, v193
	v_add_f32_e32 v186, v186, v187
	ds_bpermute_b32 v225, v120, v186
	v_mov_b32_e32 v184, v160
	s_waitcnt lgkmcnt(0)
	v_add_f32_e32 v186, v186, v225
	ds_bpermute_b32 v225, v121, v186
	s_and_saveexec_b64 s[46:47], s[40:41]
	s_cbranch_execz .Lrn_nw_0
	v_lshl_add_u32 v187, v184, 4, s26
	s_waitcnt lgkmcnt(0)
	v_add_f32_e32 v186, v186, v225
	ds_write_b32 v187, v186
.Lrn_nw_0:
	s_or_b64 exec, exec, s[46:47]
	s_waitcnt lgkmcnt(0)
	s_and_b64 vcc, exec, s[38:39]
	s_cbranch_vccnz .Lrn_wf_1
	s_waitcnt vmcnt(8)
	s_branch .Lrn_wd_1
.Lrn_wf_1:
	s_waitcnt vmcnt(4)
.Lrn_wd_1:
	v_pk_fma_f32 v[146:147], v[110:111], v[142:143], v[244:245]
	v_pk_fma_f32 v[144:145], v[108:109], v[140:141], v[242:243]
	v_pk_fma_f32 v[126:127], v[106:107], v[138:139], v[248:249]
	v_pk_fma_f32 v[124:125], v[104:105], v[136:137], v[246:247]
	v_pk_fma_f32 v[106:107], v[102:103], v[134:135], v[182:183]
	v_pk_fma_f32 v[104:105], v[100:101], v[132:133], v[180:181]
	v_pk_fma_f32 v[94:95], v[94:95], v[130:131], v[190:191]
	v_pk_fma_f32 v[92:93], v[92:93], v[128:129], v[188:189]
	s_and_b64 vcc, exec, s[38:39]
	s_cbranch_vccnz .Lrn_ns_1
	global_store_dwordx4 v[204:205], v[144:147], off
	global_store_dwordx4 v[204:205], v[124:127], off offset:64
	global_store_dwordx4 v[204:205], v[104:107], off offset:512
	global_store_dwordx4 v[204:205], v[92:95], off offset:576
.Lrn_ns_1:
	v_lshlrev_b64 v[250:251], 2, v[194:195]
	v_lshl_add_u64 v[212:213], s[0:1], 0, v[250:251]
	global_load_dwordx4 v[242:245], v[212:213], off
	global_load_dwordx4 v[246:249], v[212:213], off offset:64
	global_load_dwordx4 v[180:183], v[212:213], off offset:512
	global_load_dwordx4 v[188:191], v[212:213], off offset:576
	v_mul_f32_e32 v186, v145, v145
	v_mul_f32_e32 v187, v147, v147
	v_fmac_f32_e32 v186, v144, v144
	v_fmac_f32_e32 v187, v146, v146
	v_add_f32_e32 v186, v186, v187
	v_mul_f32_e32 v187, v125, v125
	v_mul_f32_e32 v193, v127, v127
	v_fmac_f32_e32 v187, v124, v124
	v_fmac_f32_e32 v193, v126, v126
	v_add_f32_e32 v187, v187, v193
	v_add_f32_e32 v186, v186, v187
	v_mul_f32_e32 v187, v105, v105
	v_mul_f32_e32 v193, v107, v107
	v_fmac_f32_e32 v187, v104, v104
	v_fmac_f32_e32 v193, v106, v106
	v_add_f32_e32 v187, v187, v193
	v_add_f32_e32 v186, v186, v187
	v_mul_f32_e32 v187, v93, v93
	v_mul_f32_e32 v193, v95, v95
	v_fmac_f32_e32 v187, v92, v92
	v_fmac_f32_e32 v193, v94, v94
	v_add_f32_e32 v187, v187, v193
	v_add_f32_e32 v186, v186, v187
	ds_bpermute_b32 v225, v120, v186
	v_or_b32_e32 v184, 16, v160
	s_waitcnt lgkmcnt(0)
	v_add_f32_e32 v186, v186, v225
	ds_bpermute_b32 v225, v121, v186
	s_and_saveexec_b64 s[46:47], s[40:41]
	s_cbranch_execz .Lrn_nw_1
	v_lshl_add_u32 v187, v184, 4, s26
	s_waitcnt lgkmcnt(0)
	v_add_f32_e32 v186, v186, v225
	ds_write_b32 v187, v186

.Lrn_wd_2:
	v_pk_fma_f32 v[98:99], v[98:99], v[142:143], v[228:229]
	v_pk_fma_f32 v[96:97], v[96:97], v[140:141], v[226:227]
	v_pk_fma_f32 v[90:91], v[90:91], v[138:139], v[232:233]
	v_pk_fma_f32 v[88:89], v[88:89], v[136:137], v[230:231]
	v_pk_fma_f32 v[86:87], v[86:87], v[134:135], v[236:237]
	v_pk_fma_f32 v[84:85], v[84:85], v[132:133], v[234:235]
	v_pk_fma_f32 v[78:79], v[78:79], v[130:131], v[240:241]
	v_pk_fma_f32 v[76:77], v[76:77], v[128:129], v[238:239]
	s_and_b64 vcc, exec, s[38:39]
	s_cbranch_vccnz .Lrn_ns_2
	global_store_dwordx4 v[200:201], v[96:99], off
	global_store_dwordx4 v[200:201], v[88:91], off offset:64
	global_store_dwordx4 v[200:201], v[84:87], off offset:512
	global_store_dwordx4 v[200:201], v[76:79], off offset:576
.Lrn_ns_2:
	v_lshlrev_b64 v[250:251], 2, v[174:175]
	v_lshl_add_u64 v[212:213], s[0:1], 0, v[250:251]
	global_load_dwordx4 v[226:229], v[212:213], off
	global_load_dwordx4 v[230:233], v[212:213], off offset:64
	global_load_dwordx4 v[234:237], v[212:213], off offset:512
	global_load_dwordx4 v[238:241], v[212:213], off offset:576
	v_mul_f32_e32 v186, v97, v97
	v_mul_f32_e32 v187, v99, v99
	v_fmac_f32_e32 v186, v96, v96
	v_fmac_f32_e32 v187, v98, v98
	v_add_f32_e32 v186, v186, v187
	v_mul_f32_e32 v187, v89, v89
	v_mul_f32_e32 v193, v91, v91
	v_fmac_f32_e32 v187, v88, v88
	v_fmac_f32_e32 v193, v90, v90
	v_add_f32_e32 v187, v187, v193
	v_add_f32_e32 v186, v186, v187
	v_mul_f32_e32 v187, v85, v85
	v_mul_f32_e32 v193, v87, v87
	v_fmac_f32_e32 v187, v84, v84
	v_fmac_f32_e32 v193, v86, v86
	v_add_f32_e32 v187, v187, v193
	v_add_f32_e32 v186, v186, v187
	v_mul_f32_e32 v187, v77, v77
	v_mul_f32_e32 v193, v79, v79
	v_fmac_f32_e32 v187, v76, v76
	v_fmac_f32_e32 v193, v78, v78
	v_add_f32_e32 v187, v187, v193
	v_add_f32_e32 v186, v186, v187
	ds_bpermute_b32 v225, v120, v186
	v_or_b32_e32 v184, 32, v160
	s_waitcnt lgkmcnt(0)
	v_add_f32_e32 v186, v186, v225
	ds_bpermute_b32 v225, v121, v186
	s_and_saveexec_b64 s[46:47], s[40:41]
	s_cbranch_execz .Lrn_nw_2
	v_lshl_add_u32 v187, v184, 4, s26
	s_waitcnt lgkmcnt(0)
	v_add_f32_e32 v186, v186, v225
	ds_write_b32 v187, v186

.Lrn_wd_3:
	v_pk_fma_f32 v[82:83], v[82:83], v[142:143], v[244:245]
	v_pk_fma_f32 v[80:81], v[80:81], v[140:141], v[242:243]
	v_pk_fma_f32 v[74:75], v[74:75], v[138:139], v[248:249]
	v_pk_fma_f32 v[72:73], v[72:73], v[136:137], v[246:247]
	v_pk_fma_f32 v[70:71], v[70:71], v[134:135], v[182:183]
	v_pk_fma_f32 v[68:69], v[68:69], v[132:133], v[180:181]
	v_pk_fma_f32 v[62:63], v[62:63], v[130:131], v[190:191]
	v_pk_fma_f32 v[60:61], v[60:61], v[128:129], v[188:189]
	s_and_b64 vcc, exec, s[38:39]
	s_cbranch_vccnz .Lrn_ns_3
	global_store_dwordx4 v[196:197], v[80:83], off
	global_store_dwordx4 v[196:197], v[72:75], off offset:64
	global_store_dwordx4 v[196:197], v[68:71], off offset:512
	global_store_dwordx4 v[196:197], v[60:63], off offset:576
.Lrn_ns_3:
	v_lshlrev_b64 v[250:251], 2, v[170:171]
	v_lshl_add_u64 v[212:213], s[0:1], 0, v[250:251]
	global_load_dwordx4 v[242:245], v[212:213], off
	global_load_dwordx4 v[246:249], v[212:213], off offset:64
	global_load_dwordx4 v[180:183], v[212:213], off offset:512
	global_load_dwordx4 v[188:191], v[212:213], off offset:576
	v_mul_f32_e32 v186, v81, v81
	v_mul_f32_e32 v187, v83, v83
	v_fmac_f32_e32 v186, v80, v80
	v_fmac_f32_e32 v187, v82, v82
	v_add_f32_e32 v186, v186, v187
	v_mul_f32_e32 v187, v73, v73
	v_mul_f32_e32 v193, v75, v75
	v_fmac_f32_e32 v187, v72, v72
	v_fmac_f32_e32 v193, v74, v74
	v_add_f32_e32 v187, v187, v193
	v_add_f32_e32 v186, v186, v187
	v_mul_f32_e32 v187, v69, v69
	v_mul_f32_e32 v193, v71, v71
	v_fmac_f32_e32 v187, v68, v68
	v_fmac_f32_e32 v193, v70, v70
	v_add_f32_e32 v187, v187, v193
	v_add_f32_e32 v186, v186, v187
	v_mul_f32_e32 v187, v61, v61
	v_mul_f32_e32 v193, v63, v63
	v_fmac_f32_e32 v187, v60, v60
	v_fmac_f32_e32 v193, v62, v62
	v_add_f32_e32 v187, v187, v193
	v_add_f32_e32 v186, v186, v187
	ds_bpermute_b32 v225, v120, v186
	v_or_b32_e32 v184, 48, v160
	s_waitcnt lgkmcnt(0)
	v_add_f32_e32 v186, v186, v225
	ds_bpermute_b32 v225, v121, v186
	s_and_saveexec_b64 s[46:47], s[40:41]
	s_cbranch_execz .Lrn_nw_3
	v_lshl_add_u32 v187, v184, 4, s26
	s_waitcnt lgkmcnt(0)
	v_add_f32_e32 v186, v186, v225
	ds_write_b32 v187, v186

.Lrn_wd_4:
	v_pk_fma_f32 v[66:67], v[66:67], v[142:143], v[228:229]
	v_pk_fma_f32 v[64:65], v[64:65], v[140:141], v[226:227]
	v_pk_fma_f32 v[58:59], v[58:59], v[138:139], v[232:233]
	v_pk_fma_f32 v[56:57], v[56:57], v[136:137], v[230:231]
	v_pk_fma_f32 v[54:55], v[54:55], v[134:135], v[236:237]
	v_pk_fma_f32 v[52:53], v[52:53], v[132:133], v[234:235]
	v_pk_fma_f32 v[46:47], v[46:47], v[130:131], v[240:241]
	v_pk_fma_f32 v[44:45], v[44:45], v[128:129], v[238:239]
	s_and_b64 vcc, exec, s[38:39]
	s_cbranch_vccnz .Lrn_ns_4
	global_store_dwordx4 v[176:177], v[64:67], off
	global_store_dwordx4 v[176:177], v[56:59], off offset:64
	global_store_dwordx4 v[176:177], v[52:55], off offset:512
	global_store_dwordx4 v[176:177], v[44:47], off offset:576
.Lrn_ns_4:
	v_lshlrev_b64 v[250:251], 2, v[166:167]
	v_lshl_add_u64 v[212:213], s[0:1], 0, v[250:251]
	global_load_dwordx4 v[226:229], v[212:213], off
	global_load_dwordx4 v[230:233], v[212:213], off offset:64
	global_load_dwordx4 v[234:237], v[212:213], off offset:512
	global_load_dwordx4 v[238:241], v[212:213], off offset:576
	v_mul_f32_e32 v186, v65, v65
	v_mul_f32_e32 v187, v67, v67
	v_fmac_f32_e32 v186, v64, v64
	v_fmac_f32_e32 v187, v66, v66
	v_add_f32_e32 v186, v186, v187
	v_mul_f32_e32 v187, v57, v57
	v_mul_f32_e32 v193, v59, v59
	v_fmac_f32_e32 v187, v56, v56
	v_fmac_f32_e32 v193, v58, v58
	v_add_f32_e32 v187, v187, v193
	v_add_f32_e32 v186, v186, v187
	v_mul_f32_e32 v187, v53, v53
	v_mul_f32_e32 v193, v55, v55
	v_fmac_f32_e32 v187, v52, v52
	v_fmac_f32_e32 v193, v54, v54
	v_add_f32_e32 v187, v187, v193
	v_add_f32_e32 v186, v186, v187
	v_mul_f32_e32 v187, v45, v45
	v_mul_f32_e32 v193, v47, v47
	v_fmac_f32_e32 v187, v44, v44
	v_fmac_f32_e32 v193, v46, v46
	v_add_f32_e32 v187, v187, v193
	v_add_f32_e32 v186, v186, v187
	ds_bpermute_b32 v225, v120, v186
	v_add_u32_e32 v184, 0x80, v160
	s_waitcnt lgkmcnt(0)
	v_add_f32_e32 v186, v186, v225
	ds_bpermute_b32 v225, v121, v186
	s_and_saveexec_b64 s[46:47], s[40:41]
	s_cbranch_execz .Lrn_nw_4
	v_lshl_add_u32 v187, v184, 4, s26
	s_waitcnt lgkmcnt(0)
	v_add_f32_e32 v186, v186, v225
	ds_write_b32 v187, v186

.Lrn_wd_5:
	v_pk_fma_f32 v[50:51], v[50:51], v[142:143], v[244:245]
	v_pk_fma_f32 v[48:49], v[48:49], v[140:141], v[242:243]
	v_pk_fma_f32 v[42:43], v[42:43], v[138:139], v[248:249]
	v_pk_fma_f32 v[40:41], v[40:41], v[136:137], v[246:247]
	v_pk_fma_f32 v[38:39], v[38:39], v[134:135], v[182:183]
	v_pk_fma_f32 v[36:37], v[36:37], v[132:133], v[180:181]
	v_pk_fma_f32 v[34:35], v[34:35], v[130:131], v[190:191]
	v_pk_fma_f32 v[32:33], v[32:33], v[128:129], v[188:189]
	s_and_b64 vcc, exec, s[38:39]
	s_cbranch_vccnz .Lrn_ns_5
	global_store_dwordx4 v[172:173], v[48:51], off
	global_store_dwordx4 v[172:173], v[40:43], off offset:64
	global_store_dwordx4 v[172:173], v[36:39], off offset:512
	global_store_dwordx4 v[172:173], v[32:35], off offset:576
.Lrn_ns_5:
	v_lshlrev_b64 v[250:251], 2, v[162:163]
	v_lshl_add_u64 v[212:213], s[0:1], 0, v[250:251]
	global_load_dwordx4 v[242:245], v[212:213], off
	global_load_dwordx4 v[246:249], v[212:213], off offset:64
	global_load_dwordx4 v[180:183], v[212:213], off offset:512
	global_load_dwordx4 v[188:191], v[212:213], off offset:576
	v_mul_f32_e32 v186, v49, v49
	v_mul_f32_e32 v187, v51, v51
	v_fmac_f32_e32 v186, v48, v48
	v_fmac_f32_e32 v187, v50, v50
	v_add_f32_e32 v186, v186, v187
	v_mul_f32_e32 v187, v41, v41
	v_mul_f32_e32 v193, v43, v43
	v_fmac_f32_e32 v187, v40, v40
	v_fmac_f32_e32 v193, v42, v42
	v_add_f32_e32 v187, v187, v193
	v_add_f32_e32 v186, v186, v187
	v_mul_f32_e32 v187, v37, v37
	v_mul_f32_e32 v193, v39, v39
	v_fmac_f32_e32 v187, v36, v36
	v_fmac_f32_e32 v193, v38, v38
	v_add_f32_e32 v187, v187, v193
	v_add_f32_e32 v186, v186, v187
	v_mul_f32_e32 v187, v33, v33
	v_mul_f32_e32 v193, v35, v35
	v_fmac_f32_e32 v187, v32, v32
	v_fmac_f32_e32 v193, v34, v34
	v_add_f32_e32 v187, v187, v193
	v_add_f32_e32 v186, v186, v187
	ds_bpermute_b32 v225, v120, v186
	v_add_u32_e32 v184, 0x90, v160
	s_waitcnt lgkmcnt(0)
	v_add_f32_e32 v186, v186, v225
	ds_bpermute_b32 v225, v121, v186
	s_and_saveexec_b64 s[46:47], s[40:41]
	s_cbranch_execz .Lrn_nw_5
	v_lshl_add_u32 v187, v184, 4, s26
	s_waitcnt lgkmcnt(0)
	v_add_f32_e32 v186, v186, v225
	ds_write_b32 v187, v186

.Lrn_wd_6:
	v_pk_fma_f32 v[30:31], v[30:31], v[142:143], v[228:229]
	v_pk_fma_f32 v[28:29], v[28:29], v[140:141], v[226:227]
	v_pk_fma_f32 v[26:27], v[26:27], v[138:139], v[232:233]
	v_pk_fma_f32 v[24:25], v[24:25], v[136:137], v[230:231]
	v_pk_fma_f32 v[22:23], v[22:23], v[134:135], v[236:237]
	v_pk_fma_f32 v[20:21], v[20:21], v[132:133], v[234:235]
	v_pk_fma_f32 v[18:19], v[18:19], v[130:131], v[240:241]
	v_pk_fma_f32 v[16:17], v[16:17], v[128:129], v[238:239]
	s_and_b64 vcc, exec, s[38:39]
	s_cbranch_vccnz .Lrn_ns_6
	global_store_dwordx4 v[168:169], v[28:31], off
	global_store_dwordx4 v[168:169], v[24:27], off offset:64
	global_store_dwordx4 v[168:169], v[20:23], off offset:512
	global_store_dwordx4 v[168:169], v[16:19], off offset:576
.Lrn_ns_6:
	v_mul_f32_e32 v186, v29, v29
	v_mul_f32_e32 v187, v31, v31
	v_fmac_f32_e32 v186, v28, v28
	v_fmac_f32_e32 v187, v30, v30
	v_add_f32_e32 v186, v186, v187
	v_mul_f32_e32 v187, v25, v25
	v_mul_f32_e32 v193, v27, v27
	v_fmac_f32_e32 v187, v24, v24
	v_fmac_f32_e32 v193, v26, v26
	v_add_f32_e32 v187, v187, v193
	v_add_f32_e32 v186, v186, v187
	v_mul_f32_e32 v187, v21, v21
	v_mul_f32_e32 v193, v23, v23
	v_fmac_f32_e32 v187, v20, v20
	v_fmac_f32_e32 v193, v22, v22
	v_add_f32_e32 v187, v187, v193
	v_add_f32_e32 v186, v186, v187
	v_mul_f32_e32 v187, v17, v17
	v_mul_f32_e32 v193, v19, v19
	v_fmac_f32_e32 v187, v16, v16
	v_fmac_f32_e32 v193, v18, v18
	v_add_f32_e32 v187, v187, v193
	v_add_f32_e32 v186, v186, v187
	ds_bpermute_b32 v225, v120, v186
	v_add_u32_e32 v184, 0xa0, v160
	s_waitcnt lgkmcnt(0)
	v_add_f32_e32 v186, v186, v225
	ds_bpermute_b32 v225, v121, v186
	s_and_saveexec_b64 s[46:47], s[40:41]
	s_cbranch_execz .Lrn_nw_6
	v_lshl_add_u32 v187, v184, 4, s26
	s_waitcnt lgkmcnt(0)
	v_add_f32_e32 v186, v186, v225
	ds_write_b32 v187, v186
.Lrn_nw_6:
	s_or_b64 exec, exec, s[46:47]
	s_waitcnt lgkmcnt(0)
	s_and_b64 vcc, exec, s[38:39]
	s_cbranch_vccnz .Lrn_wf_7
	s_waitcnt vmcnt(4)
	s_branch .Lrn_wd_7

.Lrn_wd_7:
	v_pk_fma_f32 v[14:15], v[14:15], v[142:143], v[244:245]
	v_pk_fma_f32 v[12:13], v[12:13], v[140:141], v[242:243]
	v_pk_fma_f32 v[10:11], v[10:11], v[138:139], v[248:249]
	v_pk_fma_f32 v[8:9], v[8:9], v[136:137], v[246:247]
	v_pk_fma_f32 v[6:7], v[6:7], v[134:135], v[182:183]
	v_pk_fma_f32 v[4:5], v[4:5], v[132:133], v[180:181]
	v_pk_fma_f32 v[2:3], v[2:3], v[130:131], v[190:191]
	v_pk_fma_f32 v[0:1], v[0:1], v[128:129], v[188:189]
	s_and_b64 vcc, exec, s[38:39]
	s_cbranch_vccnz .Lrn_ns_7
	global_store_dwordx4 v[164:165], v[12:15], off
	global_store_dwordx4 v[164:165], v[8:11], off offset:64
	global_store_dwordx4 v[164:165], v[4:7], off offset:512
	global_store_dwordx4 v[164:165], v[0:3], off offset:576
.Lrn_ns_7:
	v_mul_f32_e32 v186, v13, v13
	v_mul_f32_e32 v187, v15, v15
	v_fmac_f32_e32 v186, v12, v12
	v_fmac_f32_e32 v187, v14, v14
	v_add_f32_e32 v186, v186, v187
	v_mul_f32_e32 v187, v9, v9
	v_mul_f32_e32 v193, v11, v11
	v_fmac_f32_e32 v187, v8, v8
	v_fmac_f32_e32 v193, v10, v10
	v_add_f32_e32 v187, v187, v193
	v_add_f32_e32 v186, v186, v187
	v_mul_f32_e32 v187, v5, v5
	v_mul_f32_e32 v193, v7, v7
	v_fmac_f32_e32 v187, v4, v4
	v_fmac_f32_e32 v193, v6, v6
	v_add_f32_e32 v187, v187, v193
	v_add_f32_e32 v186, v186, v187
	v_mul_f32_e32 v187, v1, v1
	v_mul_f32_e32 v193, v3, v3
	v_fmac_f32_e32 v187, v0, v0
	v_fmac_f32_e32 v193, v2, v2
	v_add_f32_e32 v187, v187, v193
	v_add_f32_e32 v186, v186, v187
	ds_bpermute_b32 v225, v120, v186
	v_add_u32_e32 v184, 0xb0, v160
	s_waitcnt lgkmcnt(0)
	v_add_f32_e32 v186, v186, v225
	ds_bpermute_b32 v225, v121, v186
	s_and_saveexec_b64 s[0:1], s[40:41]
	s_cbranch_execz .Lrn_nw_7
	v_lshl_add_u32 v187, v184, 4, s26
	s_waitcnt lgkmcnt(0)
	v_add_f32_e32 v186, v186, v225
	ds_write_b32 v187, v186
.Lrn_nw_7:
	s_or_b64 exec, exec, s[0:1]
	s_waitcnt lgkmcnt(0)
	v_mov_b64_e32 v[180:181], 0x240
	v_mov_b64_e32 v[182:183], 0x23f
	v_mov_b64_e32 v[186:187], 0x41f
	v_mov_b64_e32 v[188:189], 0xc0
	v_mov_b64_e32 v[190:191], 0xbf
	s_waitcnt lgkmcnt(0)
	s_barrier
	v_and_b32_e32 v100, 31, v192
	s_waitcnt lgkmcnt(0)
	v_lshl_or_b32 v102, s34, 5, v100
	v_cmp_gt_u32_e64 s[0:1], 32, v224
	v_lshl_add_u32 v100, s22, 8, v102
	s_and_saveexec_b64 s[36:37], s[0:1]
	s_cbranch_execz .LBB0_914
	v_lshl_add_u32 v101, v102, 4, 0
	ds_read_b128 v[108:111], v101
	v_ashrrev_i32_e32 v101, 31, v100
	s_ashr_i32 s63, s62, 31
	s_waitcnt lgkmcnt(0)
	v_mov_b32_e32 v112, v109
	v_mov_b32_e32 v113, v110
	v_mov_b32_e32 v109, v111
	v_pk_add_f32 v[108:109], v[112:113], v[108:109]
	v_lshl_add_u64 v[110:111], v[100:101], 4, s[60:61]
	v_pk_add_f32 v[108:109], v[108:109], v[108:109] op_sel:[0,1] op_sel_hi:[1,0]
	v_lshl_add_u64 v[110:111], s[62:63], 2, v[110:111]
	global_store_dword v[110:111], v108, off sc1
